# q/k max-norms for the FoX bound computed in the in-proj GEMM epilogue from the bf16-rounded tile (same values, same per-token summation order); foxsum pass now only sums the log-forget gate
# speedup vs baseline: 1.0213x; 1.0109x over previous
.LBB0_106:
	s_mov_b32 s28, s24
	s_mov_b32 s29, s25
	v_mov_b32_e32 v152, 0
	v_mov_b32_e32 v153, 0
	v_add_u32_e32 v140, s25, v238
	v_ashrrev_i32_e32 v141, 31, v140
	s_movk_i32 s0, 0x1618
	v_or_b32_e32 v138, s24, v239
	v_lshl_add_u64 v[136:137], v[140:141], 1, s[56:57]
	v_cmp_gt_i32_e64 s[0:1], s0, v140
	v_cvt_pk_bf16_f32 v140, v112, v113
	v_cvt_pk_bf16_f32 v141, v114, v115
	v_cvt_pk_bf16_f32 v114, v116, v117
	v_cvt_pk_bf16_f32 v115, v118, v119
	v_add_u32_e32 v112, 0xc000, v240
	v_cvt_pk_bf16_f32 v96, v96, v97
	v_cvt_pk_bf16_f32 v97, v98, v99
	v_cvt_pk_bf16_f32 v98, v100, v101
	v_cvt_pk_bf16_f32 v99, v102, v103
	s_waitcnt vmcnt(0)
	ds_write2_b64 v112, v[140:141], v[114:115] offset1:2
	v_cvt_pk_bf16_f32 v114, v120, v121
	v_cvt_pk_bf16_f32 v115, v122, v123
	v_cvt_pk_bf16_f32 v116, v124, v125
	v_cvt_pk_bf16_f32 v117, v126, v127
	ds_write2_b64 v112, v[114:115], v[116:117] offset0:4 offset1:6
	ds_write2_b64 v112, v[96:97], v[98:99] offset0:8 offset1:10
	v_cvt_pk_bf16_f32 v96, v104, v105
	v_cvt_pk_bf16_f32 v97, v106, v107
	v_cvt_pk_bf16_f32 v98, v108, v109
	v_cvt_pk_bf16_f32 v99, v110, v111
	ds_write2_b64 v112, v[96:97], v[98:99] offset0:12 offset1:14
	s_and_saveexec_b64 s[6:7], s[0:1]
	s_cbranch_execz .LBB0_108
	ds_read_b128 v[96:99], v241 offset:49152
	v_mad_i64_i32 v[100:101], s[24:25], v138, s13, v[136:137]
	v_add_co_u32_e32 v102, vcc, 0x16000, v100
	s_waitcnt lgkmcnt(0)
	s_cmp_lt_u32 s29, 0x400
	s_cbranch_scc0 .Lgn_s0
	v_lshlrev_b32_e32 v144, 16, v96
	v_and_b32_e32 v145, 0xffff0000, v96
	v_mul_f32_e32 v146, v144, v144
	v_fmac_f32_e32 v146, v145, v145
	v_lshlrev_b32_e32 v144, 16, v97
	v_and_b32_e32 v145, 0xffff0000, v97
	v_fmac_f32_e32 v146, v144, v144
	v_fmac_f32_e32 v146, v145, v145
	v_lshlrev_b32_e32 v144, 16, v98
	v_and_b32_e32 v145, 0xffff0000, v98
	v_fmac_f32_e32 v146, v144, v144
	v_fmac_f32_e32 v146, v145, v145
	v_lshlrev_b32_e32 v144, 16, v99
	v_and_b32_e32 v145, 0xffff0000, v99
	v_fmac_f32_e32 v146, v144, v144
	v_fmac_f32_e32 v146, v145, v145
	s_nop 1
	v_add_f32_dpp v146, v146, v146 quad_perm:[1,0,3,2] row_mask:0xf bank_mask:0xf
	s_nop 1
	v_add_f32_dpp v146, v146, v146 quad_perm:[2,3,0,1] row_mask:0xf bank_mask:0xf
	s_nop 1
	v_add_f32_dpp v146, v146, v146 row_half_mirror row_mask:0xf bank_mask:0xf
	s_nop 0
	v_max_f32_e32 v152, v152, v146
.Lgn_s0:
	global_store_dwordx4 v[100:101], v[96:99], off
	ds_read_b128 v[96:99], v241 offset:50304
	v_addc_co_u32_e32 v103, vcc, 0, v101, vcc
	s_waitcnt lgkmcnt(0)
	s_cmp_lt_u32 s29, 0x400
	s_cbranch_scc0 .Lgn_s1
	v_lshlrev_b32_e32 v144, 16, v96
	v_and_b32_e32 v145, 0xffff0000, v96
	v_mul_f32_e32 v146, v144, v144
	v_fmac_f32_e32 v146, v145, v145
	v_lshlrev_b32_e32 v144, 16, v97
	v_and_b32_e32 v145, 0xffff0000, v97
	v_fmac_f32_e32 v146, v144, v144
	v_fmac_f32_e32 v146, v145, v145
	v_lshlrev_b32_e32 v144, 16, v98
	v_and_b32_e32 v145, 0xffff0000, v98
	v_fmac_f32_e32 v146, v144, v144
	v_fmac_f32_e32 v146, v145, v145
	v_lshlrev_b32_e32 v144, 16, v99
	v_and_b32_e32 v145, 0xffff0000, v99
	v_fmac_f32_e32 v146, v144, v144
	v_fmac_f32_e32 v146, v145, v145
	s_nop 1
	v_add_f32_dpp v146, v146, v146 quad_perm:[1,0,3,2] row_mask:0xf bank_mask:0xf
	s_nop 1
	v_add_f32_dpp v146, v146, v146 quad_perm:[2,3,0,1] row_mask:0xf bank_mask:0xf
	s_nop 1
	v_add_f32_dpp v146, v146, v146 row_half_mirror row_mask:0xf bank_mask:0xf
	s_nop 0
	v_max_f32_e32 v152, v152, v146
.Lgn_s1:
	global_store_dwordx4 v[102:103], v[96:99], off offset:384
	ds_read_b128 v[96:99], v241 offset:51456
	v_add_co_u32_e32 v102, vcc, 0x2c000, v100
	s_nop 1
	v_addc_co_u32_e32 v103, vcc, 0, v101, vcc
	s_waitcnt lgkmcnt(0)
	s_cmp_lt_u32 s29, 0x400
	s_cbranch_scc0 .Lgn_s2
	v_lshlrev_b32_e32 v144, 16, v96
	v_and_b32_e32 v145, 0xffff0000, v96
	v_mul_f32_e32 v146, v144, v144
	v_fmac_f32_e32 v146, v145, v145
	v_lshlrev_b32_e32 v144, 16, v97
	v_and_b32_e32 v145, 0xffff0000, v97
	v_fmac_f32_e32 v146, v144, v144
	v_fmac_f32_e32 v146, v145, v145
	v_lshlrev_b32_e32 v144, 16, v98
	v_and_b32_e32 v145, 0xffff0000, v98
	v_fmac_f32_e32 v146, v144, v144
	v_fmac_f32_e32 v146, v145, v145
	v_lshlrev_b32_e32 v144, 16, v99
	v_and_b32_e32 v145, 0xffff0000, v99
	v_fmac_f32_e32 v146, v144, v144
	v_fmac_f32_e32 v146, v145, v145
	s_nop 1
	v_add_f32_dpp v146, v146, v146 quad_perm:[1,0,3,2] row_mask:0xf bank_mask:0xf
	s_nop 1
	v_add_f32_dpp v146, v146, v146 quad_perm:[2,3,0,1] row_mask:0xf bank_mask:0xf
	s_nop 1
	v_add_f32_dpp v146, v146, v146 row_half_mirror row_mask:0xf bank_mask:0xf
	s_nop 0
	v_max_f32_e32 v152, v152, v146
.Lgn_s2:
	global_store_dwordx4 v[102:103], v[96:99], off offset:768
	ds_read_b128 v[96:99], v241 offset:52608
	v_add_co_u32_e32 v100, vcc, 0x42000, v100
	s_nop 1
	v_addc_co_u32_e32 v101, vcc, 0, v101, vcc
	s_waitcnt lgkmcnt(0)
	s_cmp_lt_u32 s29, 0x400
	s_cbranch_scc0 .Lgn_s3
	v_lshlrev_b32_e32 v144, 16, v96
	v_and_b32_e32 v145, 0xffff0000, v96
	v_mul_f32_e32 v146, v144, v144
	v_fmac_f32_e32 v146, v145, v145
	v_lshlrev_b32_e32 v144, 16, v97
	v_and_b32_e32 v145, 0xffff0000, v97
	v_fmac_f32_e32 v146, v144, v144
	v_fmac_f32_e32 v146, v145, v145
	v_lshlrev_b32_e32 v144, 16, v98
	v_and_b32_e32 v145, 0xffff0000, v98
	v_fmac_f32_e32 v146, v144, v144
	v_fmac_f32_e32 v146, v145, v145
	v_lshlrev_b32_e32 v144, 16, v99
	v_and_b32_e32 v145, 0xffff0000, v99
	v_fmac_f32_e32 v146, v144, v144
	v_fmac_f32_e32 v146, v145, v145
	s_nop 1
	v_add_f32_dpp v146, v146, v146 quad_perm:[1,0,3,2] row_mask:0xf bank_mask:0xf
	s_nop 1
	v_add_f32_dpp v146, v146, v146 quad_perm:[2,3,0,1] row_mask:0xf bank_mask:0xf
	s_nop 1
	v_add_f32_dpp v146, v146, v146 row_half_mirror row_mask:0xf bank_mask:0xf
	s_nop 0
	v_max_f32_e32 v152, v152, v146
.Lgn_s3:
	global_store_dwordx4 v[100:101], v[96:99], off offset:1152
.LBB0_108:
	s_or_b64 exec, exec, s[6:7]
	v_cvt_pk_bf16_f32 v80, v80, v81
	v_cvt_pk_bf16_f32 v81, v82, v83
	v_cvt_pk_bf16_f32 v82, v84, v85
	v_cvt_pk_bf16_f32 v83, v86, v87
	v_cvt_pk_bf16_f32 v64, v64, v65
	v_cvt_pk_bf16_f32 v65, v66, v67
	v_cvt_pk_bf16_f32 v66, v68, v69
	v_cvt_pk_bf16_f32 v67, v70, v71
	ds_write2_b64 v112, v[80:81], v[82:83] offset1:2
	v_cvt_pk_bf16_f32 v80, v88, v89
	v_cvt_pk_bf16_f32 v81, v90, v91
	v_cvt_pk_bf16_f32 v82, v92, v93
	v_cvt_pk_bf16_f32 v83, v94, v95
	ds_write2_b64 v112, v[80:81], v[82:83] offset0:4 offset1:6
	ds_write2_b64 v112, v[64:65], v[66:67] offset0:8 offset1:10
	v_cvt_pk_bf16_f32 v64, v72, v73
	v_cvt_pk_bf16_f32 v65, v74, v75
	v_cvt_pk_bf16_f32 v66, v76, v77
	v_cvt_pk_bf16_f32 v67, v78, v79
	ds_write2_b64 v112, v[64:65], v[66:67] offset0:12 offset1:14
	s_and_saveexec_b64 s[6:7], s[0:1]
	s_cbranch_execz .LBB0_110
	v_or_b32_e32 v64, 32, v138
	v_mad_i64_i32 v[68:69], s[24:25], v64, s13, v[136:137]
	ds_read_b128 v[64:67], v241 offset:49152
	v_add_co_u32_e32 v70, vcc, 0x16000, v68
	s_waitcnt lgkmcnt(0)
	s_cmp_lt_u32 s29, 0x400
	s_cbranch_scc0 .Lgn_s4
	v_lshlrev_b32_e32 v144, 16, v64
	v_and_b32_e32 v145, 0xffff0000, v64
	v_mul_f32_e32 v146, v144, v144
	v_fmac_f32_e32 v146, v145, v145
	v_lshlrev_b32_e32 v144, 16, v65
	v_and_b32_e32 v145, 0xffff0000, v65
	v_fmac_f32_e32 v146, v144, v144
	v_fmac_f32_e32 v146, v145, v145
	v_lshlrev_b32_e32 v144, 16, v66
	v_and_b32_e32 v145, 0xffff0000, v66
	v_fmac_f32_e32 v146, v144, v144
	v_fmac_f32_e32 v146, v145, v145
	v_lshlrev_b32_e32 v144, 16, v67
	v_and_b32_e32 v145, 0xffff0000, v67
	v_fmac_f32_e32 v146, v144, v144
	v_fmac_f32_e32 v146, v145, v145
	s_nop 1
	v_add_f32_dpp v146, v146, v146 quad_perm:[1,0,3,2] row_mask:0xf bank_mask:0xf
	s_nop 1
	v_add_f32_dpp v146, v146, v146 quad_perm:[2,3,0,1] row_mask:0xf bank_mask:0xf
	s_nop 1
	v_add_f32_dpp v146, v146, v146 row_half_mirror row_mask:0xf bank_mask:0xf
	s_nop 0
	v_max_f32_e32 v152, v152, v146
.Lgn_s4:
	global_store_dwordx4 v[68:69], v[64:67], off
	ds_read_b128 v[64:67], v241 offset:50304
	v_addc_co_u32_e32 v71, vcc, 0, v69, vcc
	s_waitcnt lgkmcnt(0)
	s_cmp_lt_u32 s29, 0x400
	s_cbranch_scc0 .Lgn_s5
	v_lshlrev_b32_e32 v144, 16, v64
	v_and_b32_e32 v145, 0xffff0000, v64
	v_mul_f32_e32 v146, v144, v144
	v_fmac_f32_e32 v146, v145, v145
	v_lshlrev_b32_e32 v144, 16, v65
	v_and_b32_e32 v145, 0xffff0000, v65
	v_fmac_f32_e32 v146, v144, v144
	v_fmac_f32_e32 v146, v145, v145
	v_lshlrev_b32_e32 v144, 16, v66
	v_and_b32_e32 v145, 0xffff0000, v66
	v_fmac_f32_e32 v146, v144, v144
	v_fmac_f32_e32 v146, v145, v145
	v_lshlrev_b32_e32 v144, 16, v67
	v_and_b32_e32 v145, 0xffff0000, v67
	v_fmac_f32_e32 v146, v144, v144
	v_fmac_f32_e32 v146, v145, v145
	s_nop 1
	v_add_f32_dpp v146, v146, v146 quad_perm:[1,0,3,2] row_mask:0xf bank_mask:0xf
	s_nop 1
	v_add_f32_dpp v146, v146, v146 quad_perm:[2,3,0,1] row_mask:0xf bank_mask:0xf
	s_nop 1
	v_add_f32_dpp v146, v146, v146 row_half_mirror row_mask:0xf bank_mask:0xf
	s_nop 0
	v_max_f32_e32 v152, v152, v146
.Lgn_s5:
	global_store_dwordx4 v[70:71], v[64:67], off offset:384
	ds_read_b128 v[64:67], v241 offset:51456
	v_add_co_u32_e32 v70, vcc, 0x2c000, v68
	s_nop 1
	v_addc_co_u32_e32 v71, vcc, 0, v69, vcc
	s_waitcnt lgkmcnt(0)
	s_cmp_lt_u32 s29, 0x400
	s_cbranch_scc0 .Lgn_s6
	v_lshlrev_b32_e32 v144, 16, v64
	v_and_b32_e32 v145, 0xffff0000, v64
	v_mul_f32_e32 v146, v144, v144
	v_fmac_f32_e32 v146, v145, v145
	v_lshlrev_b32_e32 v144, 16, v65
	v_and_b32_e32 v145, 0xffff0000, v65
	v_fmac_f32_e32 v146, v144, v144
	v_fmac_f32_e32 v146, v145, v145
	v_lshlrev_b32_e32 v144, 16, v66
	v_and_b32_e32 v145, 0xffff0000, v66
	v_fmac_f32_e32 v146, v144, v144
	v_fmac_f32_e32 v146, v145, v145
	v_lshlrev_b32_e32 v144, 16, v67
	v_and_b32_e32 v145, 0xffff0000, v67
	v_fmac_f32_e32 v146, v144, v144
	v_fmac_f32_e32 v146, v145, v145
	s_nop 1
	v_add_f32_dpp v146, v146, v146 quad_perm:[1,0,3,2] row_mask:0xf bank_mask:0xf
	s_nop 1
	v_add_f32_dpp v146, v146, v146 quad_perm:[2,3,0,1] row_mask:0xf bank_mask:0xf
	s_nop 1
	v_add_f32_dpp v146, v146, v146 row_half_mirror row_mask:0xf bank_mask:0xf
	s_nop 0
	v_max_f32_e32 v152, v152, v146
.Lgn_s6:
	global_store_dwordx4 v[70:71], v[64:67], off offset:768
	ds_read_b128 v[64:67], v241 offset:52608
	v_add_co_u32_e32 v68, vcc, 0x42000, v68
	s_nop 1
	v_addc_co_u32_e32 v69, vcc, 0, v69, vcc
	s_waitcnt lgkmcnt(0)
	s_cmp_lt_u32 s29, 0x400
	s_cbranch_scc0 .Lgn_s7
	v_lshlrev_b32_e32 v144, 16, v64
	v_and_b32_e32 v145, 0xffff0000, v64
	v_mul_f32_e32 v146, v144, v144
	v_fmac_f32_e32 v146, v145, v145
	v_lshlrev_b32_e32 v144, 16, v65
	v_and_b32_e32 v145, 0xffff0000, v65
	v_fmac_f32_e32 v146, v144, v144
	v_fmac_f32_e32 v146, v145, v145
	v_lshlrev_b32_e32 v144, 16, v66
	v_and_b32_e32 v145, 0xffff0000, v66
	v_fmac_f32_e32 v146, v144, v144
	v_fmac_f32_e32 v146, v145, v145
	v_lshlrev_b32_e32 v144, 16, v67
	v_and_b32_e32 v145, 0xffff0000, v67
	v_fmac_f32_e32 v146, v144, v144
	v_fmac_f32_e32 v146, v145, v145
	s_nop 1
	v_add_f32_dpp v146, v146, v146 quad_perm:[1,0,3,2] row_mask:0xf bank_mask:0xf
	s_nop 1
	v_add_f32_dpp v146, v146, v146 quad_perm:[2,3,0,1] row_mask:0xf bank_mask:0xf
	s_nop 1
	v_add_f32_dpp v146, v146, v146 row_half_mirror row_mask:0xf bank_mask:0xf
	s_nop 0
	v_max_f32_e32 v152, v152, v146
.Lgn_s7:
	global_store_dwordx4 v[68:69], v[64:67], off offset:1152
.LBB0_110:
	s_or_b64 exec, exec, s[6:7]
	v_cvt_pk_bf16_f32 v48, v48, v49
	v_cvt_pk_bf16_f32 v49, v50, v51
	v_cvt_pk_bf16_f32 v50, v52, v53
	v_cvt_pk_bf16_f32 v51, v54, v55
	v_cvt_pk_bf16_f32 v32, v32, v33
	v_cvt_pk_bf16_f32 v33, v34, v35
	v_cvt_pk_bf16_f32 v34, v36, v37
	v_cvt_pk_bf16_f32 v35, v38, v39
	ds_write2_b64 v112, v[48:49], v[50:51] offset1:2
	v_cvt_pk_bf16_f32 v48, v56, v57
	v_cvt_pk_bf16_f32 v49, v58, v59
	v_cvt_pk_bf16_f32 v50, v60, v61
	v_cvt_pk_bf16_f32 v51, v62, v63
	ds_write2_b64 v112, v[48:49], v[50:51] offset0:4 offset1:6
	ds_write2_b64 v112, v[32:33], v[34:35] offset0:8 offset1:10
	v_cvt_pk_bf16_f32 v32, v40, v41
	v_cvt_pk_bf16_f32 v33, v42, v43
	v_cvt_pk_bf16_f32 v34, v44, v45
	v_cvt_pk_bf16_f32 v35, v46, v47
	ds_write2_b64 v112, v[32:33], v[34:35] offset0:12 offset1:14
	s_and_saveexec_b64 s[6:7], s[0:1]
	s_cbranch_execz .LBB0_112
	v_or_b32_e32 v32, 64, v138
	v_mad_i64_i32 v[36:37], s[24:25], v32, s13, v[136:137]
	ds_read_b128 v[32:35], v241 offset:49152
	v_add_co_u32_e32 v38, vcc, 0x16000, v36
	s_waitcnt lgkmcnt(0)
	s_cmp_lt_u32 s29, 0x400
	s_cbranch_scc0 .Lgn_s8
	v_lshlrev_b32_e32 v144, 16, v32
	v_and_b32_e32 v145, 0xffff0000, v32
	v_mul_f32_e32 v146, v144, v144
	v_fmac_f32_e32 v146, v145, v145
	v_lshlrev_b32_e32 v144, 16, v33
	v_and_b32_e32 v145, 0xffff0000, v33
	v_fmac_f32_e32 v146, v144, v144
	v_fmac_f32_e32 v146, v145, v145
	v_lshlrev_b32_e32 v144, 16, v34
	v_and_b32_e32 v145, 0xffff0000, v34
	v_fmac_f32_e32 v146, v144, v144
	v_fmac_f32_e32 v146, v145, v145
	v_lshlrev_b32_e32 v144, 16, v35
	v_and_b32_e32 v145, 0xffff0000, v35
	v_fmac_f32_e32 v146, v144, v144
	v_fmac_f32_e32 v146, v145, v145
	s_nop 1
	v_add_f32_dpp v146, v146, v146 quad_perm:[1,0,3,2] row_mask:0xf bank_mask:0xf
	s_nop 1
	v_add_f32_dpp v146, v146, v146 quad_perm:[2,3,0,1] row_mask:0xf bank_mask:0xf
	s_nop 1
	v_add_f32_dpp v146, v146, v146 row_half_mirror row_mask:0xf bank_mask:0xf
	s_nop 0
	v_max_f32_e32 v153, v153, v146
.Lgn_s8:
	global_store_dwordx4 v[36:37], v[32:35], off
	ds_read_b128 v[32:35], v241 offset:50304
	v_addc_co_u32_e32 v39, vcc, 0, v37, vcc
	s_waitcnt lgkmcnt(0)
	s_cmp_lt_u32 s29, 0x400
	s_cbranch_scc0 .Lgn_s9
	v_lshlrev_b32_e32 v144, 16, v32
	v_and_b32_e32 v145, 0xffff0000, v32
	v_mul_f32_e32 v146, v144, v144
	v_fmac_f32_e32 v146, v145, v145
	v_lshlrev_b32_e32 v144, 16, v33
	v_and_b32_e32 v145, 0xffff0000, v33
	v_fmac_f32_e32 v146, v144, v144
	v_fmac_f32_e32 v146, v145, v145
	v_lshlrev_b32_e32 v144, 16, v34
	v_and_b32_e32 v145, 0xffff0000, v34
	v_fmac_f32_e32 v146, v144, v144
	v_fmac_f32_e32 v146, v145, v145
	v_lshlrev_b32_e32 v144, 16, v35
	v_and_b32_e32 v145, 0xffff0000, v35
	v_fmac_f32_e32 v146, v144, v144
	v_fmac_f32_e32 v146, v145, v145
	s_nop 1
	v_add_f32_dpp v146, v146, v146 quad_perm:[1,0,3,2] row_mask:0xf bank_mask:0xf
	s_nop 1
	v_add_f32_dpp v146, v146, v146 quad_perm:[2,3,0,1] row_mask:0xf bank_mask:0xf
	s_nop 1
	v_add_f32_dpp v146, v146, v146 row_half_mirror row_mask:0xf bank_mask:0xf
	s_nop 0
	v_max_f32_e32 v153, v153, v146
.Lgn_s9:
	global_store_dwordx4 v[38:39], v[32:35], off offset:384
	ds_read_b128 v[32:35], v241 offset:51456
	v_add_co_u32_e32 v38, vcc, 0x2c000, v36
	s_nop 1
	v_addc_co_u32_e32 v39, vcc, 0, v37, vcc
	s_waitcnt lgkmcnt(0)
	s_cmp_lt_u32 s29, 0x400
	s_cbranch_scc0 .Lgn_s10
	v_lshlrev_b32_e32 v144, 16, v32
	v_and_b32_e32 v145, 0xffff0000, v32
	v_mul_f32_e32 v146, v144, v144
	v_fmac_f32_e32 v146, v145, v145
	v_lshlrev_b32_e32 v144, 16, v33
	v_and_b32_e32 v145, 0xffff0000, v33
	v_fmac_f32_e32 v146, v144, v144
	v_fmac_f32_e32 v146, v145, v145
	v_lshlrev_b32_e32 v144, 16, v34
	v_and_b32_e32 v145, 0xffff0000, v34
	v_fmac_f32_e32 v146, v144, v144
	v_fmac_f32_e32 v146, v145, v145
	v_lshlrev_b32_e32 v144, 16, v35
	v_and_b32_e32 v145, 0xffff0000, v35
	v_fmac_f32_e32 v146, v144, v144
	v_fmac_f32_e32 v146, v145, v145
	s_nop 1
	v_add_f32_dpp v146, v146, v146 quad_perm:[1,0,3,2] row_mask:0xf bank_mask:0xf
	s_nop 1
	v_add_f32_dpp v146, v146, v146 quad_perm:[2,3,0,1] row_mask:0xf bank_mask:0xf
	s_nop 1
	v_add_f32_dpp v146, v146, v146 row_half_mirror row_mask:0xf bank_mask:0xf
	s_nop 0
	v_max_f32_e32 v153, v153, v146
.Lgn_s10:
	global_store_dwordx4 v[38:39], v[32:35], off offset:768
	ds_read_b128 v[32:35], v241 offset:52608
	v_add_co_u32_e32 v36, vcc, 0x42000, v36
	s_nop 1
	v_addc_co_u32_e32 v37, vcc, 0, v37, vcc
	s_waitcnt lgkmcnt(0)
	s_cmp_lt_u32 s29, 0x400
	s_cbranch_scc0 .Lgn_s11
	v_lshlrev_b32_e32 v144, 16, v32
	v_and_b32_e32 v145, 0xffff0000, v32
	v_mul_f32_e32 v146, v144, v144
	v_fmac_f32_e32 v146, v145, v145
	v_lshlrev_b32_e32 v144, 16, v33
	v_and_b32_e32 v145, 0xffff0000, v33
	v_fmac_f32_e32 v146, v144, v144
	v_fmac_f32_e32 v146, v145, v145
	v_lshlrev_b32_e32 v144, 16, v34
	v_and_b32_e32 v145, 0xffff0000, v34
	v_fmac_f32_e32 v146, v144, v144
	v_fmac_f32_e32 v146, v145, v145
	v_lshlrev_b32_e32 v144, 16, v35
	v_and_b32_e32 v145, 0xffff0000, v35
	v_fmac_f32_e32 v146, v144, v144
	v_fmac_f32_e32 v146, v145, v145
	s_nop 1
	v_add_f32_dpp v146, v146, v146 quad_perm:[1,0,3,2] row_mask:0xf bank_mask:0xf
	s_nop 1
	v_add_f32_dpp v146, v146, v146 quad_perm:[2,3,0,1] row_mask:0xf bank_mask:0xf
	s_nop 1
	v_add_f32_dpp v146, v146, v146 row_half_mirror row_mask:0xf bank_mask:0xf
	s_nop 0
	v_max_f32_e32 v153, v153, v146
.Lgn_s11:
	global_store_dwordx4 v[36:37], v[32:35], off offset:1152
.LBB0_112:
	s_or_b64 exec, exec, s[6:7]
	v_cvt_pk_bf16_f32 v16, v16, v17
	v_cvt_pk_bf16_f32 v17, v18, v19
	v_cvt_pk_bf16_f32 v18, v20, v21
	v_cvt_pk_bf16_f32 v19, v22, v23
	v_cvt_pk_bf16_f32 v0, v0, v1
	v_cvt_pk_bf16_f32 v1, v2, v3
	v_cvt_pk_bf16_f32 v2, v4, v5
	v_cvt_pk_bf16_f32 v3, v6, v7
	ds_write2_b64 v112, v[16:17], v[18:19] offset1:2
	v_cvt_pk_bf16_f32 v16, v24, v25
	v_cvt_pk_bf16_f32 v17, v26, v27
	v_cvt_pk_bf16_f32 v18, v28, v29
	v_cvt_pk_bf16_f32 v19, v30, v31
	ds_write2_b64 v112, v[16:17], v[18:19] offset0:4 offset1:6
	ds_write2_b64 v112, v[0:1], v[2:3] offset0:8 offset1:10
	v_cvt_pk_bf16_f32 v0, v8, v9
	v_cvt_pk_bf16_f32 v1, v10, v11
	v_cvt_pk_bf16_f32 v2, v12, v13
	v_cvt_pk_bf16_f32 v3, v14, v15
	ds_write2_b64 v112, v[0:1], v[2:3] offset0:12 offset1:14
	s_and_saveexec_b64 s[6:7], s[0:1]
	s_cbranch_execz .LBB0_94
	v_or_b32_e32 v0, 0x60, v138
	v_mad_i64_i32 v[4:5], s[0:1], v0, s13, v[136:137]
	ds_read_b128 v[0:3], v241 offset:49152
	v_add_co_u32_e32 v6, vcc, 0x16000, v4
	s_waitcnt lgkmcnt(0)
	s_cmp_lt_u32 s29, 0x400
	s_cbranch_scc0 .Lgn_s12
	v_lshlrev_b32_e32 v144, 16, v0
	v_and_b32_e32 v145, 0xffff0000, v0
	v_mul_f32_e32 v146, v144, v144
	v_fmac_f32_e32 v146, v145, v145
	v_lshlrev_b32_e32 v144, 16, v1
	v_and_b32_e32 v145, 0xffff0000, v1
	v_fmac_f32_e32 v146, v144, v144
	v_fmac_f32_e32 v146, v145, v145
	v_lshlrev_b32_e32 v144, 16, v2
	v_and_b32_e32 v145, 0xffff0000, v2
	v_fmac_f32_e32 v146, v144, v144
	v_fmac_f32_e32 v146, v145, v145
	v_lshlrev_b32_e32 v144, 16, v3
	v_and_b32_e32 v145, 0xffff0000, v3
	v_fmac_f32_e32 v146, v144, v144
	v_fmac_f32_e32 v146, v145, v145
	s_nop 1
	v_add_f32_dpp v146, v146, v146 quad_perm:[1,0,3,2] row_mask:0xf bank_mask:0xf
	s_nop 1
	v_add_f32_dpp v146, v146, v146 quad_perm:[2,3,0,1] row_mask:0xf bank_mask:0xf
	s_nop 1
	v_add_f32_dpp v146, v146, v146 row_half_mirror row_mask:0xf bank_mask:0xf
	s_nop 0
	v_max_f32_e32 v153, v153, v146
.Lgn_s12:
	global_store_dwordx4 v[4:5], v[0:3], off
	ds_read_b128 v[0:3], v241 offset:50304
	v_addc_co_u32_e32 v7, vcc, 0, v5, vcc
	s_waitcnt lgkmcnt(0)
	s_cmp_lt_u32 s29, 0x400
	s_cbranch_scc0 .Lgn_s13
	v_lshlrev_b32_e32 v144, 16, v0
	v_and_b32_e32 v145, 0xffff0000, v0
	v_mul_f32_e32 v146, v144, v144
	v_fmac_f32_e32 v146, v145, v145
	v_lshlrev_b32_e32 v144, 16, v1
	v_and_b32_e32 v145, 0xffff0000, v1
	v_fmac_f32_e32 v146, v144, v144
	v_fmac_f32_e32 v146, v145, v145
	v_lshlrev_b32_e32 v144, 16, v2
	v_and_b32_e32 v145, 0xffff0000, v2
	v_fmac_f32_e32 v146, v144, v144
	v_fmac_f32_e32 v146, v145, v145
	v_lshlrev_b32_e32 v144, 16, v3
	v_and_b32_e32 v145, 0xffff0000, v3
	v_fmac_f32_e32 v146, v144, v144
	v_fmac_f32_e32 v146, v145, v145
	s_nop 1
	v_add_f32_dpp v146, v146, v146 quad_perm:[1,0,3,2] row_mask:0xf bank_mask:0xf
	s_nop 1
	v_add_f32_dpp v146, v146, v146 quad_perm:[2,3,0,1] row_mask:0xf bank_mask:0xf
	s_nop 1
	v_add_f32_dpp v146, v146, v146 row_half_mirror row_mask:0xf bank_mask:0xf
	s_nop 0
	v_max_f32_e32 v153, v153, v146
.Lgn_s13:
	global_store_dwordx4 v[6:7], v[0:3], off offset:384
	ds_read_b128 v[0:3], v241 offset:51456
	v_add_co_u32_e32 v6, vcc, 0x2c000, v4
	s_nop 1
	v_addc_co_u32_e32 v7, vcc, 0, v5, vcc
	s_waitcnt lgkmcnt(0)
	s_cmp_lt_u32 s29, 0x400
	s_cbranch_scc0 .Lgn_s14
	v_lshlrev_b32_e32 v144, 16, v0
	v_and_b32_e32 v145, 0xffff0000, v0
	v_mul_f32_e32 v146, v144, v144
	v_fmac_f32_e32 v146, v145, v145
	v_lshlrev_b32_e32 v144, 16, v1
	v_and_b32_e32 v145, 0xffff0000, v1
	v_fmac_f32_e32 v146, v144, v144
	v_fmac_f32_e32 v146, v145, v145
	v_lshlrev_b32_e32 v144, 16, v2
	v_and_b32_e32 v145, 0xffff0000, v2
	v_fmac_f32_e32 v146, v144, v144
	v_fmac_f32_e32 v146, v145, v145
	v_lshlrev_b32_e32 v144, 16, v3
	v_and_b32_e32 v145, 0xffff0000, v3
	v_fmac_f32_e32 v146, v144, v144
	v_fmac_f32_e32 v146, v145, v145
	s_nop 1
	v_add_f32_dpp v146, v146, v146 quad_perm:[1,0,3,2] row_mask:0xf bank_mask:0xf
	s_nop 1
	v_add_f32_dpp v146, v146, v146 quad_perm:[2,3,0,1] row_mask:0xf bank_mask:0xf
	s_nop 1
	v_add_f32_dpp v146, v146, v146 row_half_mirror row_mask:0xf bank_mask:0xf
	s_nop 0
	v_max_f32_e32 v153, v153, v146
.Lgn_s14:
	global_store_dwordx4 v[6:7], v[0:3], off offset:768
	ds_read_b128 v[0:3], v241 offset:52608
	v_add_co_u32_e32 v4, vcc, 0x42000, v4
	s_nop 1
	v_addc_co_u32_e32 v5, vcc, 0, v5, vcc
	s_waitcnt lgkmcnt(0)
	s_cmp_lt_u32 s29, 0x400
	s_cbranch_scc0 .Lgn_s15
	v_lshlrev_b32_e32 v144, 16, v0
	v_and_b32_e32 v145, 0xffff0000, v0
	v_mul_f32_e32 v146, v144, v144
	v_fmac_f32_e32 v146, v145, v145
	v_lshlrev_b32_e32 v144, 16, v1
	v_and_b32_e32 v145, 0xffff0000, v1
	v_fmac_f32_e32 v146, v144, v144
	v_fmac_f32_e32 v146, v145, v145
	v_lshlrev_b32_e32 v144, 16, v2
	v_and_b32_e32 v145, 0xffff0000, v2
	v_fmac_f32_e32 v146, v144, v144
	v_fmac_f32_e32 v146, v145, v145
	v_lshlrev_b32_e32 v144, 16, v3
	v_and_b32_e32 v145, 0xffff0000, v3
	v_fmac_f32_e32 v146, v144, v144
	v_fmac_f32_e32 v146, v145, v145
	s_nop 1
	v_add_f32_dpp v146, v146, v146 quad_perm:[1,0,3,2] row_mask:0xf bank_mask:0xf
	s_nop 1
	v_add_f32_dpp v146, v146, v146 quad_perm:[2,3,0,1] row_mask:0xf bank_mask:0xf
	s_nop 1
	v_add_f32_dpp v146, v146, v146 row_half_mirror row_mask:0xf bank_mask:0xf
	s_nop 0
	v_max_f32_e32 v153, v153, v146
.Lgn_s15:
	global_store_dwordx4 v[4:5], v[0:3], off offset:1152
	s_cmp_lt_u32 s29, 0x400
	s_cbranch_scc0 .Lgn_done
	v_readlane_b32 s0, v245, 38
	v_readlane_b32 s1, v245, 39
	v_max_f32_dpp v144, v152, v152 row_ror:8 row_mask:0xf bank_mask:0xf
	v_max_f32_dpp v145, v153, v153 row_ror:8 row_mask:0xf bank_mask:0xf
	s_nop 0
	v_max_f32_e32 v152, v152, v144
	v_max_f32_e32 v153, v153, v145
	s_nop 1
	v_readlane_b32 s24, v152, 16
	v_readlane_b32 s25, v153, 16
	s_nop 1
	v_max_f32_e32 v144, s24, v152
	v_max_f32_e32 v145, s25, v153
	v_readlane_b32 s24, v152, 32
	v_readlane_b32 s25, v153, 32
	s_nop 1
	v_max_f32_e32 v144, s24, v144
	v_max_f32_e32 v145, s25, v145
	v_readlane_b32 s24, v152, 48
	v_readlane_b32 s25, v153, 48
	s_nop 1
	v_max_f32_e32 v144, s24, v144
	v_max_f32_e32 v145, s25, v145
	v_readfirstlane_b32 s24, v239
	v_readfirstlane_b32 s25, v238
	s_nop 1
	s_add_u32 s28, s24, s28
	s_add_u32 s29, s25, s29
	s_mov_b32 s24, 0
	s_cmp_ge_u32 s28, 0x2080
	s_addc_u32 s24, s24, 0
	s_cmp_ge_u32 s28, 0x4100
	s_addc_u32 s24, s24, 0
	s_cmp_ge_u32 s28, 0x6180
	s_addc_u32 s24, s24, 0
	s_mul_i32 s25, s24, 0x2080
	s_sub_u32 s28, s28, s25
	s_lshr_b32 s28, s28, 6
	s_lshr_b32 s25, s29, 6
	s_and_b32 s25, s25, 7
	s_lshl_b32 s24, s24, 3
	s_add_u32 s24, s24, s25
	s_mul_i32 s24, s24, 0x82
	s_add_u32 s24, s24, s28
	s_lshl_b32 s24, s24, 3
	s_lshr_b32 s29, s29, 9
	s_lshl_b32 s29, s29, 2
	s_add_u32 s24, s24, s29
	v_mov_b32_e32 v146, s24
	s_mov_b64 s[24:25], exec
	s_mov_b64 exec, 1
	global_store_dword v146, v144, s[0:1]
	global_store_dword v146, v145, s[0:1] offset:8
	s_mov_b64 exec, s[24:25]
.Lgn_done:
	s_branch .LBB0_94
.LBB0_114:
	v_readlane_b32 s18, v244, 13
	v_readlane_b32 s22, v244, 15
	v_readlane_b32 s19, v244, 14
	v_readlane_b32 s23, v244, 16
	s_movk_i32 s16, 0xfc1

.LBB0_129:
	v_mul_u32_u24_sdwa v0, v42, s16 dst_sel:DWORD dst_unused:UNUSED_PAD src0_sel:WORD_0 src1_sel:DWORD
	v_readlane_b32 s2, v245, 10
	v_readlane_b32 s3, v245, 11
	v_lshrrev_b32_e32 v1, 19, v0
	v_mul_lo_u16_e32 v1, 0x82, v1
	v_sub_u16_e32 v1, v42, v1
	v_lshlrev_b16_e32 v1, 6, v1
	v_lshrrev_b32_e32 v2, 22, v0
	v_mul_u32_u24_e32 v2, 0x2080, v2
	v_bfe_u32 v0, v0, 19, 3
	v_lshrrev_b32_e32 v8, 3, v176
	v_add3_u32 v8, v2, v1, v8
	v_or_b32_e32 v1, v176, v1
	v_add_u32_e32 v4, v2, v1
	v_mul_u32_u24_e32 v4, 0x1618, v4
	v_or_b32_e32 v4, v4, v0
	v_mov_b32_e32 v5, v179
	v_lshl_add_u64 v[4:5], v[4:5], 1, s[56:57]
	global_load_ushort v6, v[4:5], off offset:3072
	v_or_b32_e32 v4, s6, v0
	v_mov_b32_e32 v5, v179
	v_lshl_add_u64 v[4:5], v[4:5], 2, s[2:3]
	global_load_dword v7, v[4:5], off
	v_mul_u32_u24_e32 v8, 0x1618, v8
	v_mov_b32_e32 v9, v179
	v_lshl_add_u64 v[8:9], v[8:9], 1, s[56:57]
	v_lshlrev_b32_e32 v10, 7, v0
	v_and_b32_e32 v11, 7, v176
	v_lshl_add_u32 v10, v11, 4, v10
	v_mov_b32_e32 v11, v179
	v_lshl_add_u64 v[8:9], v[8:9], 0, v[10:11]
	s_mov_b32 s10, 0x16180
	s_mov_b32 s11, 0
	s_waitcnt vmcnt(0)
	v_lshlrev_b32_e32 v6, 16, v6
	v_add_f32_e32 v6, v7, v6
	v_mul_f32_e64 v2, |v6|, s98
	v_exp_f32_e32 v2, v2
	v_min_f32_e32 v3, 0, v6
	v_add_f32_e32 v2, 1.0, v2
	v_log_f32_e32 v2, v2
	v_cmp_gt_u32_e32 vcc, s36, v1
	v_fmac_f32_e32 v3, 0xbf317218, v2
	s_nop 0
	v_cndmask_b32_e64 v3, v3, 0, vcc
	ds_bpermute_b32 v1, v36, v3
	s_waitcnt lgkmcnt(0)
	v_add_f32_e32 v1, v3, v1
	ds_bpermute_b32 v2, v37, v1
	s_waitcnt lgkmcnt(0)
	v_add_f32_e32 v1, v1, v2
	ds_bpermute_b32 v2, v38, v1
	s_waitcnt lgkmcnt(0)
	v_add_f32_e32 v1, v1, v2
	ds_bpermute_b32 v2, v39, v1
	s_waitcnt lgkmcnt(0)
	v_add_f32_e32 v1, v1, v2
	ds_bpermute_b32 v2, v40, v1
	s_waitcnt lgkmcnt(0)
	v_add_f32_e32 v43, v1, v2
	ds_bpermute_b32 v44, v41, v43
	s_waitcnt lgkmcnt(0)
	v_add_f32_e32 v4, v43, v44
	s_mov_b64 s[2:3], exec
	v_readlane_b32 s10, v245, 63
	v_readlane_b32 s11, v244, 0
	s_and_b64 s[10:11], s[2:3], s[10:11]
	s_mov_b64 exec, s[10:11]
	global_store_dword v[32:33], v4, off
	s_branch .LBB0_128
